# adds: nt cache policy on the attention output and log-sum-exp stores
# baseline (speedup 1.0000x reference)
; #define LAS __attribute__((address_space(3)))
; DI void attn_phase(LAS unsigned char* lds, bf16_t* QKV, float* LSE, const float* qg, const float* kg, const float* relb, int G, int bid) {
;     ...
;         qf[0] = *(const LAS bf16x8*)(Qs + (16 * w + fr) * 72 + 8 * fq); qf[1] = *(const LAS bf16x8*)(Qs + (16 * w + fr) * 72 + 32 + 8 * fq);
;         f32x4 sc[9];
; #pragma unroll
;         for (int i = 0; i < 9; ++i) { const int tau = w + i; const int kr = ((((n + 1 + (tau >> 3)) & 1) << 7) | ((tau & 7) << 4)) + fr; f32x4 acc = (f32x4){0.f, 0.f, 0.f, 0.f};
;             const bf16x8 a0 = *(const LAS bf16x8*)(Ks + kr * 72 + 8 * fq), a1 = *(const LAS bf16x8*)(Ks + kr * 72 + 32 + 8 * fq);
;             acc = __builtin_amdgcn_mfma_f32_16x16x32_bf16(a0, qf[0], acc, 0, 0, 0);
;             acc = __builtin_amdgcn_mfma_f32_16x16x32_bf16(a1, qf[1], acc, 0, 0, 0);
;             sc[i] = acc; }
;         float mx = -INFINITY;
;         const LAS float* tb = tab + (16 + fr - 4 * fq - 3);
;         const int dlt = fr - 4 * fq;
;         float bv[9][4];
; #pragma unroll
;         for (int i = 0; i < 9; ++i)
; #pragma unroll
;             for (int j = 0; j < 4; ++j) bv[i][j] = tb[16 * (8 - i) + (3 - j)];
; #pragma unroll
;         for (int i = 0; i < 9; ++i)
; #pragma unroll
;             for (int j = 0; j < 4; ++j) asm volatile("" : "+v"(bv[i][j]));
; #pragma unroll
;         for (int i = 0; i < 9; ++i) { const bool tv = (n > 0) || (w + i >= 8);
; #pragma unroll
;             for (int j = 0; j < 4; ++j) { bool valid = tv;
;                 if (i == 0) valid = valid && (dlt - j <= 0);
;                 if (i == 8) valid = valid && (dlt - j >= 0);
;                 const float v = valid ? sc[i][j] + bv[i][j] : -INFINITY; sc[i][j] = v; mx = fmaxf(mx, v); } }
.LBB0_328:
	s_not_b32 s2, s92
	v_add_lshl_u32 v57, v61, s2, 7
	v_and_or_b32 v57, v57, s30, v106
	v_mad_u32_u24 v57, v57, s25, v46
	ds_read_b128 v[122:125], v57 offset:18432
	ds_read_b128 v[126:129], v48
	ds_read_b128 v[130:133], v48 offset:64
	ds_read_b128 v[134:137], v57 offset:18496
	v_add_lshl_u32 v110, v62, s2, 7
	v_and_or_b32 v110, v110, s30, v107
	v_mad_u32_u24 v110, v110, s25, v46
	s_waitcnt lgkmcnt(0)
	v_mfma_f32_16x16x32_bf16 v[122:125], v[122:125], v[126:129], 0
	ds_read_b128 v[138:141], v110 offset:18432
	ds_read_b128 v[142:145], v110 offset:18496
	v_add_lshl_u32 v57, v63, s2, 7
	v_and_or_b32 v57, v57, s30, v108
	v_mad_u32_u24 v57, v57, s25, v46
	s_waitcnt lgkmcnt(1)
	v_mfma_f32_16x16x32_bf16 v[138:141], v[138:141], v[126:129], 0
	s_cmp_lg_u32 s92, 0
	s_cselect_b64 s[88:89], -1, 0
	s_or_b64 s[82:83], s[44:45], s[88:89]
	v_mfma_f32_16x16x32_bf16 v[122:125], v[134:137], v[130:133], v[122:125]
	ds_read_b128 v[134:137], v57 offset:18432
	s_and_b64 vcc, s[82:83], s[46:47]
	s_add_i32 s92, s92, 1
	s_waitcnt lgkmcnt(1)
	v_mfma_f32_16x16x32_bf16 v[138:141], v[142:145], v[130:133], v[138:141]
	ds_read_b128 v[142:145], v57 offset:18496
	v_add_lshl_u32 v57, v64, s2, 7
	v_and_or_b32 v57, v57, s30, v109
	s_waitcnt lgkmcnt(1)
	v_mfma_f32_16x16x32_bf16 v[134:137], v[134:137], v[126:129], 0
	v_mad_u32_u24 v57, v57, s25, v46
	s_waitcnt lgkmcnt(0)
	v_mfma_f32_16x16x32_bf16 v[134:137], v[142:145], v[130:133], v[134:137]
	ds_read_b128 v[142:145], v57 offset:18432
	ds_read_b128 v[146:149], v57 offset:18496
	v_add_lshl_u32 v57, v65, s2, 7
	v_and_or_b32 v57, v57, s30, v114
	v_mad_u32_u24 v57, v57, s25, v46
	s_waitcnt lgkmcnt(1)
	v_mfma_f32_16x16x32_bf16 v[142:145], v[142:145], v[126:129], 0
	ds_read_b128 v[150:153], v57 offset:18432
	s_waitcnt lgkmcnt(1)
	v_mfma_f32_16x16x32_bf16 v[142:145], v[146:149], v[130:133], v[142:145]
	ds_read_b128 v[146:149], v57 offset:18496
	v_add_lshl_u32 v57, v66, s2, 7
	v_and_or_b32 v57, v57, s30, v115
	s_waitcnt lgkmcnt(1)
	v_mfma_f32_16x16x32_bf16 v[150:153], v[150:153], v[126:129], 0
	v_mad_u32_u24 v57, v57, s25, v46
	s_waitcnt lgkmcnt(0)
	v_mfma_f32_16x16x32_bf16 v[146:149], v[146:149], v[130:133], v[150:153]
	s_nop 4
	ds_read_b128 v[150:153], v57 offset:18432
	ds_read_b128 v[154:157], v57 offset:18496
	v_add_lshl_u32 v57, v67, s2, 7
	v_and_or_b32 v57, v57, s30, v116
	v_mad_u32_u24 v57, v57, s25, v46
	s_waitcnt lgkmcnt(1)
	v_mfma_f32_16x16x32_bf16 v[150:153], v[150:153], v[126:129], 0
	ds_read_b128 v[158:161], v57 offset:18432
	s_waitcnt lgkmcnt(1)
	v_mfma_f32_16x16x32_bf16 v[150:153], v[154:157], v[130:133], v[150:153]
	ds_read_b128 v[154:157], v57 offset:18496
	v_add_lshl_u32 v57, v68, s2, 7
	v_and_or_b32 v57, v57, s30, v117
	s_waitcnt lgkmcnt(1)
	v_mfma_f32_16x16x32_bf16 v[158:161], v[158:161], v[126:129], 0
	v_mad_u32_u24 v57, v57, s25, v46
	s_waitcnt lgkmcnt(0)
	v_mfma_f32_16x16x32_bf16 v[154:157], v[154:157], v[130:133], v[158:161]
	s_nop 4
	ds_read_b128 v[158:161], v57 offset:18432
	ds_read_b128 v[162:165], v57 offset:18496
	v_add_lshl_u32 v57, v69, s2, 7
	v_and_or_b32 v57, v57, s30, v118
	v_mad_u32_u24 v57, v57, s25, v46
	s_waitcnt lgkmcnt(1)
	v_mfma_f32_16x16x32_bf16 v[158:161], v[158:161], v[126:129], 0
	ds_read_b128 v[166:169], v57 offset:18432
	s_mov_b32 s2, 0xff800000
	s_waitcnt lgkmcnt(1)
	v_mfma_f32_16x16x32_bf16 v[158:161], v[162:165], v[130:133], v[158:161]
	ds_read_b128 v[162:165], v57 offset:18496
	s_waitcnt lgkmcnt(1)
	v_mfma_f32_16x16x32_bf16 v[126:129], v[166:169], v[126:129], 0
	ds_read2_b32 v[110:111], v31 offset0:127 offset1:128
	ds_read2_b32 v[166:167], v31 offset0:125 offset1:126
	ds_read2_b32 v[168:169], v31 offset0:111 offset1:112
	ds_read2_b32 v[170:171], v31 offset0:109 offset1:110
	s_waitcnt lgkmcnt(4)
	v_mfma_f32_16x16x32_bf16 v[126:129], v[162:165], v[130:133], v[126:129]
	ds_read2_b32 v[130:131], v31 offset0:95 offset1:96
	ds_read2_b32 v[132:133], v31 offset0:93 offset1:94
	ds_read2_b32 v[162:163], v31 offset0:79 offset1:80
	ds_read2_b32 v[164:165], v31 offset0:77 offset1:78
	ds_read2_b32 v[172:173], v31 offset0:63 offset1:64
	ds_read2_b32 v[174:175], v31 offset0:61 offset1:62
	ds_read2_b32 v[176:177], v31 offset0:47 offset1:48
	ds_read2_b32 v[178:179], v31 offset0:45 offset1:46
	ds_read2_b32 v[180:181], v31 offset0:31 offset1:32
	ds_read2_b32 v[182:183], v31 offset0:29 offset1:30
	ds_read2_b32 v[184:185], v31 offset0:15 offset1:16
	ds_read2_b32 v[186:187], v31 offset0:13 offset1:14
	ds_read2_b32 v[188:189], v70 offset1:1
	ds_read2_b32 v[192:193], v35 offset1:1
	s_waitcnt lgkmcnt(14)
	s_nop 0
	v_add_f32_e32 v57, v122, v111
	v_cndmask_b32_e32 v57, v228, v57, vcc
	v_add_f32_e32 v110, v123, v110
	s_and_b64 vcc, s[82:83], s[48:49]
	v_cndmask_b32_e32 v110, v228, v110, vcc
	v_add_f32_e32 v112, v124, v167
	s_and_b64 vcc, s[82:83], s[50:51]
	v_cndmask_b32_e32 v112, v228, v112, vcc
	v_add_f32_e32 v121, v125, v166
	s_and_b64 vcc, s[82:83], s[52:53]
	v_cndmask_b32_e32 v122, v228, v121, vcc
	v_add_f32_e32 v121, v138, v169
	s_or_b64 vcc, s[54:55], s[88:89]
	v_cndmask_b32_e32 v123, v228, v121, vcc
	v_add_f32_e32 v121, v139, v168
	v_cndmask_b32_e32 v124, v228, v121, vcc
	v_add_f32_e32 v121, v140, v171
	v_cndmask_b32_e32 v125, v228, v121, vcc
	v_add_f32_e32 v121, v141, v170
	s_waitcnt lgkmcnt(13)
	v_cndmask_b32_e32 v138, v228, v121, vcc
	v_add_f32_e32 v121, v134, v131
	s_or_b64 vcc, s[56:57], s[88:89]
	v_cndmask_b32_e32 v131, v228, v121, vcc
	v_add_f32_e32 v121, v135, v130
	s_waitcnt lgkmcnt(12)
	v_cndmask_b32_e32 v130, v228, v121, vcc
	v_add_f32_e32 v121, v136, v133
	v_cndmask_b32_e32 v133, v228, v121, vcc
	v_add_f32_e32 v121, v137, v132
	s_waitcnt lgkmcnt(11)
; #define LAS __attribute__((address_space(3)))
; DI unsigned pk2(float lo, float hi) { f32x2n v = {lo, hi}; bf16x2n b = __builtin_convertvector(v, bf16x2n); return __builtin_bit_cast(unsigned, b); }
; DI float x16_sum(float x) { const unsigned u = __builtin_bit_cast(unsigned, x); auto r = __builtin_amdgcn_permlane16_swap(u, u, false, false); return __builtin_bit_cast(float, (unsigned)r[0]) + __builtin_bit_cast(float, (unsigned)r[1]); }
; DI void attn_phase(LAS unsigned char* lds, bf16_t* QKV, float* LSE, const float* qg, const float* kg, const float* relb, int G, int bid) {
;     ...
;         for (int i = 0; i < 9; ++i) { const bool tv = (n > 0) || (w + i >= 8);
; #pragma unroll
;             for (int j = 0; j < 4; ++j) { bool valid = tv;
;                 if (i == 0) valid = valid && (dlt - j <= 0);
;                 if (i == 8) valid = valid && (dlt - j >= 0);
;                 const float v = valid ? sc[i][j] + bv[i][j] : -INFINITY; sc[i][j] = v; mx = fmaxf(mx, v); } }
;         mx = x16_max(mx); mx = x32_max(mx);
;         float sum = 0.f;
; #pragma unroll
;         for (int i = 0; i < 9; ++i)
; #pragma unroll
;             for (int j = 0; j < 4; ++j) { const float p = __builtin_amdgcn_exp2f(sc[i][j] - mx); sc[i][j] = p; sum += p; }
;         sum = x16_sum(sum); sum = x32_sum(sum);
;         f32x4 o[4];
; #pragma unroll
;         for (int et = 0; et < 4; ++et) o[et] = (f32x4){0.f, 0.f, 0.f, 0.f};
; #pragma unroll
;         for (int pi = 0; pi < 5; ++pi) { const int ia = 2 * pi, ib = (2 * pi + 1 < 9) ? 2 * pi + 1 : 8;
;             u32x4 pw; pw.x = pk2(sc[ia][0], sc[ia][1]); pw.y = pk2(sc[ia][2], sc[ia][3]);
;             if (2 * pi + 1 < 9) { pw.z = pk2(sc[ib][0], sc[ib][1]); pw.w = pk2(sc[ib][2], sc[ib][3]); } else { pw.z = 0u; pw.w = 0u; }
;             const bf16x8 pb = __builtin_bit_cast(bf16x8, pw);
;             const int ta = w + ia; int tb = w + 2 * pi + 1; if (tb > 15) tb = 15;
;             const int ca = ((((n + 1 + (ta >> 3)) & 1) << 7) | ((ta & 7) << 4)) + 4 * fq, cb = ((((n + 1 + (tb >> 3)) & 1) << 7) | ((tb & 7) << 4)) + 4 * fq;
; #pragma unroll
;             for (int et = 0; et < 4; ++et) { const LAS bf16_t* vr = Vt + (16 * et + fr) * 264;
;                 const u32x2 lo = *(const LAS u32x2*)(vr + ca), hi = *(const LAS u32x2*)(vr + cb);
	v_cndmask_b32_e32 v132, v228, v121, vcc
	v_add_f32_e32 v121, v142, v163
	s_or_b64 vcc, s[58:59], s[88:89]
	v_cndmask_b32_e32 v134, v228, v121, vcc
	v_add_f32_e32 v121, v143, v162
	s_waitcnt lgkmcnt(10)
	v_cndmask_b32_e32 v135, v228, v121, vcc
	v_add_f32_e32 v121, v144, v165
	v_cndmask_b32_e32 v136, v228, v121, vcc
	v_add_f32_e32 v121, v145, v164
	s_waitcnt lgkmcnt(9)
	v_cndmask_b32_e32 v137, v228, v121, vcc
	v_add_f32_e32 v121, v146, v173
	s_or_b64 vcc, s[60:61], s[88:89]
	v_cndmask_b32_e32 v139, v228, v121, vcc
	v_add_f32_e32 v121, v147, v172
	s_waitcnt lgkmcnt(8)
	v_cndmask_b32_e32 v140, v228, v121, vcc
	v_add_f32_e32 v121, v148, v175
	v_cndmask_b32_e32 v141, v228, v121, vcc
	v_add_f32_e32 v121, v149, v174
	s_waitcnt lgkmcnt(7)
	v_max3_f32 v111, v57, s2, v110
	v_cndmask_b32_e32 v142, v228, v121, vcc
	v_add_f32_e32 v121, v150, v177
	s_or_b64 vcc, s[62:63], s[88:89]
	v_max3_f32 v111, v111, v112, v122
	v_cndmask_b32_e32 v143, v228, v121, vcc
	v_add_f32_e32 v121, v151, v176
	s_waitcnt lgkmcnt(6)
	v_max3_f32 v111, v111, v123, v124
	v_cndmask_b32_e32 v144, v228, v121, vcc
	v_add_f32_e32 v121, v152, v179
	v_max3_f32 v111, v111, v125, v138
	v_cndmask_b32_e32 v145, v228, v121, vcc
	v_add_f32_e32 v121, v153, v178
	s_waitcnt lgkmcnt(5)
	v_max3_f32 v111, v111, v131, v130
	v_cndmask_b32_e32 v146, v228, v121, vcc
	v_add_f32_e32 v121, v154, v181
	s_or_b64 vcc, s[64:65], s[88:89]
	v_max3_f32 v111, v111, v133, v132
	v_cndmask_b32_e32 v147, v228, v121, vcc
	v_add_f32_e32 v121, v155, v180
	s_waitcnt lgkmcnt(4)
	v_max3_f32 v111, v111, v134, v135
	v_cndmask_b32_e32 v148, v228, v121, vcc
	v_add_f32_e32 v121, v156, v183
	v_max3_f32 v111, v111, v136, v137
	v_cndmask_b32_e32 v149, v228, v121, vcc
	v_add_f32_e32 v121, v157, v182
	s_waitcnt lgkmcnt(3)
	v_max3_f32 v111, v111, v139, v140
	v_cndmask_b32_e32 v150, v228, v121, vcc
	v_add_f32_e32 v121, v158, v185
	s_or_b64 vcc, s[66:67], s[88:89]
	v_max3_f32 v111, v111, v141, v142
	v_cndmask_b32_e32 v151, v228, v121, vcc
	v_add_f32_e32 v121, v159, v184
	s_waitcnt lgkmcnt(2)
	v_max3_f32 v111, v111, v143, v144
	v_cndmask_b32_e32 v152, v228, v121, vcc
	v_add_f32_e32 v121, v160, v187
	v_max3_f32 v111, v111, v145, v146
	v_cndmask_b32_e32 v154, v228, v121, vcc
	v_add_f32_e32 v121, v161, v186
	s_or_b64 s[82:83], s[68:69], s[88:89]
	s_waitcnt lgkmcnt(1)
	v_max3_f32 v111, v111, v147, v148
	v_cndmask_b32_e32 v155, v228, v121, vcc
	v_add_f32_e32 v121, v126, v189
	s_and_b64 vcc, s[82:83], s[70:71]
	v_max3_f32 v111, v111, v149, v150
	v_cndmask_b32_e32 v156, v228, v121, vcc
	v_add_f32_e32 v121, v127, v188
	s_and_b64 vcc, s[82:83], s[72:73]
	s_waitcnt lgkmcnt(0)
	v_max3_f32 v111, v111, v151, v152
	v_cndmask_b32_e32 v157, v228, v121, vcc
	v_add_f32_e32 v121, v128, v193
	s_and_b64 vcc, s[82:83], s[74:75]
	v_max3_f32 v111, v111, v154, v155
	v_cndmask_b32_e32 v158, v228, v121, vcc
	v_add_f32_e32 v121, v129, v192
	s_and_b64 vcc, s[82:83], s[76:77]
	v_max3_f32 v111, v111, v156, v157
	v_cndmask_b32_e32 v159, v228, v121, vcc
	v_max3_f32 v111, v111, v158, v159
	v_mov_b32_e32 v121, v111
	s_nop 1
	v_permlane16_swap_b32_e32 v111, v121
	v_max_f32_e32 v121, v121, v121
	v_max_f32_e32 v111, v111, v111
	v_max_f32_e32 v111, v111, v121
	v_mov_b32_e32 v121, v111
	s_nop 1
	v_permlane32_swap_b32_e32 v111, v121
	v_max_f32_e32 v121, v121, v121
	v_max_f32_e32 v111, v111, v111
	v_max_f32_e32 v121, v111, v121
	v_sub_f32_e32 v122, v122, v121
	v_exp_f32_e32 v126, v122
	v_sub_f32_e32 v122, v123, v121
	v_exp_f32_e32 v127, v122
	v_sub_f32_e32 v122, v124, v121
	v_exp_f32_e32 v124, v122
	v_sub_f32_e32 v122, v125, v121
	v_exp_f32_e32 v125, v122
	v_sub_f32_e32 v122, v138, v121
	v_exp_f32_e32 v128, v122
	v_sub_f32_e32 v122, v131, v121
	v_sub_f32_e32 v57, v57, v121
	v_exp_f32_e32 v153, v122
	v_sub_f32_e32 v122, v130, v121
	v_exp_f32_e32 v57, v57
	v_sub_f32_e32 v110, v110, v121
	v_exp_f32_e32 v160, v122
	v_sub_f32_e32 v122, v133, v121
	v_exp_f32_e32 v110, v110
	v_sub_f32_e32 v112, v112, v121
	v_exp_f32_e32 v161, v122
	v_sub_f32_e32 v122, v132, v121
	v_exp_f32_e32 v112, v112
	v_exp_f32_e32 v162, v122
	v_sub_f32_e32 v122, v134, v121
	v_exp_f32_e32 v163, v122
	v_sub_f32_e32 v122, v135, v121
	v_add_f32_e32 v111, 0, v57
	v_exp_f32_e32 v164, v122
	v_sub_f32_e32 v122, v136, v121
	v_add_f32_e32 v111, v110, v111
	v_exp_f32_e32 v165, v122
	v_sub_f32_e32 v122, v137, v121
	v_add_f32_e32 v111, v112, v111
	v_exp_f32_e32 v166, v122
	v_sub_f32_e32 v122, v139, v121
	v_add_f32_e32 v111, v126, v111
	v_exp_f32_e32 v167, v122
	v_sub_f32_e32 v122, v140, v121
	v_add_f32_e32 v111, v127, v111
	v_exp_f32_e32 v168, v122
	v_sub_f32_e32 v122, v141, v121
	v_add_f32_e32 v111, v124, v111
	v_exp_f32_e32 v169, v122
	v_sub_f32_e32 v122, v142, v121
	v_add_f32_e32 v111, v125, v111
	v_exp_f32_e32 v170, v122
	v_sub_f32_e32 v122, v143, v121
	v_add_f32_e32 v111, v128, v111
	v_exp_f32_e32 v171, v122
	v_sub_f32_e32 v122, v144, v121
	v_add_f32_e32 v111, v153, v111
	v_exp_f32_e32 v172, v122
	v_sub_f32_e32 v122, v145, v121
	v_add_f32_e32 v111, v160, v111
	v_exp_f32_e32 v173, v122
	v_sub_f32_e32 v122, v146, v121
	v_add_f32_e32 v111, v161, v111
	v_exp_f32_e32 v174, v122
	v_sub_f32_e32 v122, v147, v121
	v_add_f32_e32 v111, v162, v111
	v_exp_f32_e32 v175, v122
	v_sub_f32_e32 v122, v148, v121
	v_add_f32_e32 v111, v163, v111
	v_exp_f32_e32 v176, v122
	v_sub_f32_e32 v122, v149, v121
	v_add_f32_e32 v111, v164, v111
	v_exp_f32_e32 v177, v122
	v_cvt_pk_bf16_f32 v122, v57, v110
	v_cvt_pk_bf16_f32 v123, v112, v126
	v_add_lshl_u32 v57, s92, v61, 8
	v_add_lshl_u32 v112, s92, v71, 8
	v_add_f32_e32 v111, v165, v111
	v_and_b32_e32 v57, 0x100, v57
	v_and_b32_e32 v112, 0x100, v112
	v_add_f32_e32 v111, v166, v111
	v_cvt_pk_bf16_f32 v125, v125, v128
	v_add_u32_e32 v110, v72, v57
	v_add_u32_e32 v128, v73, v112
	v_add_f32_e32 v111, v167, v111
	v_cvt_pk_bf16_f32 v124, v127, v124
	ds_read_b64 v[126:127], v110 offset:55296
	ds_read_b64 v[128:129], v128 offset:55296
	v_add_u32_e32 v110, v74, v57
	v_add_u32_e32 v132, v75, v112
	v_add_f32_e32 v111, v168, v111
	v_sub_f32_e32 v138, v150, v121
	ds_read_b64 v[130:131], v110 offset:55296
	ds_read_b64 v[132:133], v132 offset:55296
	v_add_u32_e32 v57, v76, v57
	v_add_u32_e32 v110, v77, v112
	v_add_lshl_u32 v142, s92, v63, 8
	v_add_lshl_u32 v143, s92, v78, 8
	v_add_f32_e32 v111, v169, v111
	ds_read_b64 v[134:135], v57 offset:16896
	ds_read_b64 v[136:137], v110 offset:16896
	v_exp_f32_e32 v112, v138
	ds_read_b64 v[140:141], v110 offset:25344
	ds_read_b64 v[138:139], v57 offset:25344
	v_sub_f32_e32 v110, v151, v121
	v_and_b32_e32 v150, 0x100, v142
	v_and_b32_e32 v151, 0x100, v143
	v_add_f32_e32 v111, v170, v111
	v_add_u32_e32 v142, v79, v150
	v_add_u32_e32 v144, v80, v151
	v_add_f32_e32 v111, v171, v111
	ds_read_b64 v[142:143], v142 offset:55296
	ds_read_b64 v[144:145], v144 offset:55296
	v_add_f32_e32 v111, v172, v111
	s_waitcnt lgkmcnt(8)
; #define LAS __attribute__((address_space(3)))
; DI unsigned pk2(float lo, float hi) { f32x2n v = {lo, hi}; bf16x2n b = __builtin_convertvector(v, bf16x2n); return __builtin_bit_cast(unsigned, b); }
; DI float frcp(float x) { return __builtin_amdgcn_rcpf(x); }
; DI void attn_phase(LAS unsigned char* lds, bf16_t* QKV, float* LSE, const float* qg, const float* kg, const float* relb, int G, int bid) {
;     ...
;         for (int pi = 0; pi < 5; ++pi) { const int ia = 2 * pi, ib = (2 * pi + 1 < 9) ? 2 * pi + 1 : 8;
;             u32x4 pw; pw.x = pk2(sc[ia][0], sc[ia][1]); pw.y = pk2(sc[ia][2], sc[ia][3]);
;             if (2 * pi + 1 < 9) { pw.z = pk2(sc[ib][0], sc[ib][1]); pw.w = pk2(sc[ib][2], sc[ib][3]); } else { pw.z = 0u; pw.w = 0u; }
;             const bf16x8 pb = __builtin_bit_cast(bf16x8, pw);
;             const int ta = w + ia; int tb = w + 2 * pi + 1; if (tb > 15) tb = 15;
;             const int ca = ((((n + 1 + (ta >> 3)) & 1) << 7) | ((ta & 7) << 4)) + 4 * fq, cb = ((((n + 1 + (tb >> 3)) & 1) << 7) | ((tb & 7) << 4)) + 4 * fq;
; #pragma unroll
;             for (int et = 0; et < 4; ++et) { const LAS bf16_t* vr = Vt + (16 * et + fr) * 264;
;                 const u32x2 lo = *(const LAS u32x2*)(vr + ca), hi = *(const LAS u32x2*)(vr + cb);
;                 u32x4 aw; aw.x = lo.x; aw.y = lo.y; aw.z = hi.x; aw.w = hi.y;
;                 o[et] = __builtin_amdgcn_mfma_f32_16x16x32_bf16(__builtin_bit_cast(bf16x8, aw), pb, o[et], 0, 0, 0); } }
;         const float inv = frcp(sum);
;         bf16_t* orow = qp + (size_t)(16 * w + fr) * 1024 + 4 * fq;
; #pragma unroll
;         for (int et = 0; et < 4; ++et) { u32x2 ow; ow.x = pk2(o[et][0] * inv, o[et][1] * inv); ow.y = pk2(o[et][2] * inv, o[et][3] * inv); *(u32x2*)(orow + 16 * et) = ow; }
	v_mfma_f32_16x16x32_bf16 v[126:129], v[126:129], v[122:125], 0
	v_add_f32_e32 v111, v173, v111
	v_add_f32_e32 v111, v174, v111
	v_add_f32_e32 v111, v175, v111
	s_waitcnt lgkmcnt(6)
	v_mfma_f32_16x16x32_bf16 v[130:133], v[130:133], v[122:125], 0
	v_add_u32_e32 v146, v81, v150
	v_add_u32_e32 v148, v82, v151
	v_add_f32_e32 v57, v176, v111
	s_waitcnt lgkmcnt(4)
	v_mfma_f32_16x16x32_bf16 v[134:137], v[134:137], v[122:125], 0
	v_sub_f32_e32 v111, v152, v121
	ds_read_b64 v[146:147], v146 offset:55296
	ds_read_b64 v[148:149], v148 offset:55296
	v_exp_f32_e32 v110, v110
	s_waitcnt lgkmcnt(4)
	v_mfma_f32_16x16x32_bf16 v[122:125], v[138:141], v[122:125], 0
	v_cvt_pk_bf16_f32 v138, v153, v160
	v_cvt_pk_bf16_f32 v139, v161, v162
	v_cvt_pk_bf16_f32 v140, v163, v164
	v_cvt_pk_bf16_f32 v141, v165, v166
	v_add_u32_e32 v160, v83, v150
	v_add_u32_e32 v161, v84, v151
	ds_read_b64 v[150:151], v160 offset:16896
	ds_read_b64 v[152:153], v161 offset:16896
	s_waitcnt lgkmcnt(4)
	v_mfma_f32_16x16x32_bf16 v[126:129], v[142:145], v[138:141], v[126:129]
	ds_read_b64 v[144:145], v161 offset:25344
	ds_read_b64 v[142:143], v160 offset:25344
	v_exp_f32_e32 v111, v111
	v_add_f32_e32 v57, v177, v57
	s_waitcnt lgkmcnt(0)
	v_mfma_f32_16x16x32_bf16 v[122:125], v[142:145], v[138:141], v[122:125]
	v_add_lshl_u32 v142, s92, v65, 8
	v_add_lshl_u32 v143, s92, v85, 8
	v_add_f32_e32 v57, v112, v57
	v_mfma_f32_16x16x32_bf16 v[134:137], v[150:153], v[138:141], v[134:137]
	v_and_b32_e32 v150, 0x100, v142
	v_and_b32_e32 v151, 0x100, v143
	v_add_u32_e32 v142, v86, v150
	v_add_u32_e32 v144, v87, v151
	ds_read_b64 v[142:143], v142 offset:55296
	ds_read_b64 v[144:145], v144 offset:55296
	v_mfma_f32_16x16x32_bf16 v[130:133], v[146:149], v[138:141], v[130:133]
	v_sub_f32_e32 v146, v154, v121
	v_exp_f32_e32 v154, v146
	v_sub_f32_e32 v146, v155, v121
	v_exp_f32_e32 v155, v146
	v_cvt_pk_bf16_f32 v138, v167, v168
	v_cvt_pk_bf16_f32 v139, v169, v170
	v_cvt_pk_bf16_f32 v140, v171, v172
	v_cvt_pk_bf16_f32 v141, v173, v174
	v_add_u32_e32 v146, v88, v150
	v_add_u32_e32 v148, v89, v151
	v_add_u32_e32 v160, v90, v150
	v_add_u32_e32 v161, v91, v151
	ds_read_b64 v[146:147], v146 offset:55296
	ds_read_b64 v[148:149], v148 offset:55296
	ds_read_b64 v[150:151], v160 offset:16896
	ds_read_b64 v[152:153], v161 offset:16896
	s_waitcnt lgkmcnt(4)
	v_mfma_f32_16x16x32_bf16 v[126:129], v[142:145], v[138:141], v[126:129]
	ds_read_b64 v[144:145], v161 offset:25344
	ds_read_b64 v[142:143], v160 offset:25344
	v_add_f32_e32 v57, v110, v57
	v_add_f32_e32 v57, v111, v57
	s_waitcnt lgkmcnt(4)
	v_mfma_f32_16x16x32_bf16 v[130:133], v[146:149], v[138:141], v[130:133]
	v_sub_f32_e32 v146, v157, v121
	v_exp_f32_e32 v157, v146
	v_sub_f32_e32 v156, v156, v121
	s_waitcnt lgkmcnt(2)
	v_mfma_f32_16x16x32_bf16 v[134:137], v[150:153], v[138:141], v[134:137]
	v_exp_f32_e32 v156, v156
	v_add_f32_e32 v57, v154, v57
	v_add_f32_e32 v57, v155, v57
	s_waitcnt lgkmcnt(0)
	v_mfma_f32_16x16x32_bf16 v[122:125], v[142:145], v[138:141], v[122:125]
	v_cvt_pk_bf16_f32 v139, v177, v112
	v_cvt_pk_bf16_f32 v140, v110, v111
	v_add_lshl_u32 v110, s92, v67, 8
	v_add_lshl_u32 v112, s92, v92, 8
	v_and_b32_e32 v110, 0x100, v110
	v_and_b32_e32 v112, 0x100, v112
	v_add_u32_e32 v111, v93, v110
	v_add_u32_e32 v144, v94, v112
	ds_read_b64 v[142:143], v111 offset:55296
	ds_read_b64 v[144:145], v144 offset:55296
	v_add_u32_e32 v111, v95, v110
	v_add_u32_e32 v148, v96, v112
	v_cvt_pk_bf16_f32 v138, v175, v176
	v_cvt_pk_bf16_f32 v141, v154, v155
	ds_read_b64 v[146:147], v111 offset:55296
	ds_read_b64 v[148:149], v148 offset:55296
	v_add_u32_e32 v110, v97, v110
	v_add_u32_e32 v111, v98, v112
	ds_read_b64 v[150:151], v110 offset:16896
	ds_read_b64 v[152:153], v111 offset:16896
	s_waitcnt lgkmcnt(4)
	v_mfma_f32_16x16x32_bf16 v[126:129], v[142:145], v[138:141], v[126:129]
	ds_read_b64 v[144:145], v111 offset:25344
	ds_read_b64 v[142:143], v110 offset:25344
	v_sub_f32_e32 v112, v158, v121
	v_exp_f32_e32 v111, v112
	s_waitcnt lgkmcnt(4)
	v_mfma_f32_16x16x32_bf16 v[130:133], v[146:149], v[138:141], v[130:133]
	v_sub_f32_e32 v110, v159, v121
	v_exp_f32_e32 v112, v110
	v_add_f32_e32 v57, v156, v57
	s_waitcnt lgkmcnt(2)
	v_mfma_f32_16x16x32_bf16 v[134:137], v[150:153], v[138:141], v[134:137]
	v_add_f32_e32 v57, v157, v57
	v_add_f32_e32 v57, v111, v57
	v_add_f32_e32 v57, v112, v57
	s_waitcnt lgkmcnt(0)
	v_mfma_f32_16x16x32_bf16 v[122:125], v[142:145], v[138:141], v[122:125]
	v_add_lshl_u32 v138, s92, v69, 8
	v_add_lshl_u32 v139, s92, v99, 8
	v_and_b32_e32 v146, 0x100, v138
	v_and_b32_e32 v147, 0x100, v139
	v_add_u32_e32 v138, v100, v146
	v_add_u32_e32 v140, v101, v147
	ds_read_b64 v[138:139], v138 offset:55296
	ds_read_b64 v[140:141], v140 offset:55296
	v_add_u32_e32 v142, v102, v146
	v_add_u32_e32 v144, v103, v147
	ds_read_b64 v[142:143], v142 offset:55296
	ds_read_b64 v[144:145], v144 offset:55296
	v_cvt_pk_bf16_f32 v110, v156, v157
	v_cvt_pk_bf16_f32 v111, v111, v112
	v_mov_b32_e32 v112, v113
	v_add_u32_e32 v150, v104, v146
	v_add_u32_e32 v151, v105, v147
	ds_read_b64 v[146:147], v150 offset:16896
	ds_read_b64 v[148:149], v151 offset:16896
	s_waitcnt lgkmcnt(4)
	v_mfma_f32_16x16x32_bf16 v[126:129], v[138:141], v[110:113], v[126:129]
	v_mov_b32_e32 v152, v57
	ds_read_b64 v[140:141], v151 offset:25344
	ds_read_b64 v[138:139], v150 offset:25344
	v_permlane16_swap_b32_e32 v57, v152
	v_add_f32_e32 v57, v57, v152
	s_waitcnt lgkmcnt(4)
	v_mfma_f32_16x16x32_bf16 v[130:133], v[142:145], v[110:113], v[130:133]
	v_mov_b32_e32 v142, v57
	s_nop 1
	v_permlane32_swap_b32_e32 v57, v142
	s_waitcnt lgkmcnt(2)
	v_mfma_f32_16x16x32_bf16 v[134:137], v[146:149], v[110:113], v[134:137]
	s_waitcnt lgkmcnt(0)
	v_mfma_f32_16x16x32_bf16 v[122:125], v[138:141], v[110:113], v[122:125]
	v_add_f32_e32 v110, v57, v142
	v_rcp_f32_e32 v112, v110
	v_lshl_add_u64 v[138:139], s[96:97], 0, v[50:51]
	v_mov_b32_e32 v57, v113
	v_lshl_add_u64 v[138:139], v[138:139], 0, v[56:57]
	v_pk_mul_f32 v[126:127], v[112:113], v[126:127] op_sel_hi:[0,1]
	v_pk_mul_f32 v[128:129], v[112:113], v[128:129] op_sel_hi:[0,1]
	v_cvt_pk_bf16_f32 v126, v126, v127
	v_cvt_pk_bf16_f32 v127, v128, v129
	global_store_dwordx2 v[138:139], v[126:127], off nt
	v_pk_mul_f32 v[126:127], v[112:113], v[130:131] op_sel_hi:[0,1]
	v_pk_mul_f32 v[128:129], v[112:113], v[132:133] op_sel_hi:[0,1]
	v_cvt_pk_bf16_f32 v126, v126, v127
	v_cvt_pk_bf16_f32 v127, v128, v129
	global_store_dwordx2 v[138:139], v[126:127], off offset:32 nt
	v_pk_mul_f32 v[126:127], v[112:113], v[134:135] op_sel_hi:[0,1]
	v_pk_mul_f32 v[128:129], v[112:113], v[136:137] op_sel_hi:[0,1]
	v_pk_mul_f32 v[122:123], v[112:113], v[122:123] op_sel_hi:[0,1]
	v_pk_mul_f32 v[124:125], v[112:113], v[124:125] op_sel_hi:[0,1]
	v_cvt_pk_bf16_f32 v126, v126, v127
	v_cvt_pk_bf16_f32 v127, v128, v129
	v_cvt_pk_bf16_f32 v122, v122, v123
	v_cvt_pk_bf16_f32 v123, v124, v125
	global_store_dwordx2 v[138:139], v[126:127], off offset:64 nt
	global_store_dwordx2 v[138:139], v[122:123], off offset:96 nt
	s_and_saveexec_b64 s[88:89], s[42:43]
	s_cbranch_execz .LBB0_313
; DI void attn_phase(LAS unsigned char* lds, bf16_t* QKV, float* LSE, const float* qg, const float* kg, const float* relb, int G, int bid) {
;     ...
;         if (fq == 0) LSE[((size_t)g * TH + rowbase + 16 * w + fr) * 16 + h] = (mx + __log2f(sum)) * 0.6931471805599453f;
	v_log_f32_e32 v57, v110
	s_lshl_b64 s[0:1], s[0:1], 20
	v_lshl_add_u64 v[110:111], v[44:45], 0, s[94:95]
	s_add_u32 s0, s20, s0
	v_lshlrev_b64 v[110:111], 6, v[110:111]
	s_addc_u32 s1, s21, s1
	v_add_f32_e32 v57, v121, v57
	v_lshl_add_u64 v[110:111], s[0:1], 0, v[110:111]
	s_lshl_b32 s34, s34, 2
	v_mul_f32_e32 v57, 0x3f317218, v57
	v_lshl_add_u64 v[110:111], v[110:111], 0, s[34:35]
	global_store_dword v[110:111], v57, off nt
	s_branch .LBB0_313
